# fp8 gate units epilogue hand-written: bias pre-scaled by -log2e (exponent argument = one packed fma), packed +1 and *255; q/k tiles keep the compiler path
# speedup vs baseline: 1.0122x; 1.0059x over previous
; #define LAS __attribute__((address_space(3)))
; __device__ __forceinline__ u32x4 pk8(const f32x4 v0, const f32x4 v1) { u32x4 w; w.x = pk_f16(v0[0], v0[1]); w.y = pk_f16(v0[2], v0[3]); w.z = pk_f16(v1[0], v1[1]); w.w = pk_f16(v1[2], v1[3]); return w; }
;     __device__ __forceinline__ void operator()(const f32x4 (&acc)[2][2][4][2], const GUnit& u, int wr, int wc, int fr, int fq, LAS unsigned char*) const {
;         const int grow0 = u.pm * 256 + wr * 64 + fr, gcol0 = u.pn * 256 + wc * 32 + 8 * fq;
;         unsigned char* base = ws + B_SG; const float* bias = b_in + gcol0;
;         f32x4 bv[2][2];
;         const bool qk = u.kind != K_SG;
; #pragma unroll
;         for (int bj = 0; bj < 2; ++bj)
; #pragma unroll
;             for (int n = 0; n < 2; ++n) bv[bj][n] = *(const f32x4*)(bias + bj * 128 + 4 * n);
; #pragma unroll
;         for (int ai = 0; ai < 2; ++ai)
; #pragma unroll
;             for (int m = 0; m < 4; ++m) { unsigned char* rowp = base + (size_t)(grow0 + ai * 128 + m * 16) * 2048 + (gcol0 - 2048);
;                 if (qk) { f16* qp = (f16*)(ws + (u.kind == K_Q ? B_Q : B_K)) + (size_t)(grow0 + ai * 128 + m * 16) * 512 + (gcol0 & 511);
; #pragma unroll
;                     for (int bj = 0; bj < 2; ++bj) *(u32x4*)(qp + bj * 128) = pk8(acc[ai][bj][m][0] + bv[bj][0], acc[ai][bj][m][1] + bv[bj][1]);
;                     continue; }
.LBB0_76:
	s_nop 15
	s_nop 15
	v_mbcnt_lo_u32_b32 v18, -1, 0
	v_mbcnt_hi_u32_b32 v18, -1, v18
	s_lshl_b32 s8, s30, 8
	v_ashrrev_i32_e32 v0, 1, v18
	v_and_b32_e32 v0, -8, v0
	s_or_b32 s8, s8, s92
	v_add_u32_e32 v16, s8, v0
	v_ashrrev_i32_e32 v17, 31, v16
	v_lshl_add_u64 v[0:1], v[16:17], 2, s[14:15]
	global_load_dwordx4 v[12:15], v[0:1], off
	global_load_dwordx4 v[8:11], v[0:1], off offset:16
	global_load_dwordx4 v[4:7], v[0:1], off offset:512
	s_nop 0
	global_load_dwordx4 v[0:3], v[0:1], off offset:528
	v_and_or_b32 v18, v18, 15, s48
	s_cmp_lg_u32 s28, 3
	v_lshl_add_u32 v18, s29, 8, v18
	s_cselect_b64 s[24:25], -1, 0
	v_and_b32_e32 v20, 0x1f8, v16
	v_readlane_b32 s80, v254, 46
	v_readlane_b32 s74, v254, 48
	v_readlane_b32 s68, v254, 50
	s_mov_b64 s[8:9], -1
	v_ashrrev_i32_e32 v19, 31, v18
	s_and_b64 vcc, exec, s[24:25]
	v_lshlrev_b32_e32 v32, 1, v20
	v_readlane_b32 s81, v254, 47
	v_readlane_b32 s75, v254, 49
	v_readlane_b32 s69, v254, 51
	s_waitcnt vmcnt(0)
	s_cmp_eq_u32 s28, 3
	s_cbranch_scc1 .Lsg_mine
	v_pk_add_f32 v[26:27], v[158:159], v[12:13]
	v_pk_add_f32 v[24:25], v[154:155], v[8:9]
	v_pk_add_f32 v[22:23], v[126:127], v[4:5]
	v_pk_add_f32 v[20:21], v[122:123], v[0:1]
	s_cbranch_vccz .LBB0_78
	s_cmp_eq_u32 s28, 0
	s_cselect_b32 s8, s65, 0x7c00000
	s_add_u32 s8, s54, s8
	s_addc_u32 s9, s55, 0
	v_lshlrev_b64 v[28:29], 10, v[18:19]
	v_lshl_add_u64 v[28:29], s[8:9], 0, v[28:29]
	v_pk_add_f32 v[30:31], v[160:161], v[14:15]
	v_pk_add_f32 v[170:171], v[156:157], v[10:11]
	v_lshl_add_u64 v[168:169], v[28:29], 0, v[32:33]
	v_cvt_pk_f16_f32 v28, v26, v27
	v_cvt_pk_f16_f32 v29, v30, v31
	v_cvt_pk_f16_f32 v30, v24, v25
	v_cvt_pk_f16_f32 v31, v170, v171
	global_store_dwordx4 v[168:169], v[28:31], off
	v_pk_add_f32 v[170:171], v[124:125], v[2:3]
	s_mov_b64 s[8:9], 0
	v_pk_add_f32 v[30:31], v[128:129], v[6:7]
	v_cvt_pk_f16_f32 v28, v22, v23
	v_cvt_pk_f16_f32 v29, v30, v31
	v_cvt_pk_f16_f32 v30, v20, v21
	v_cvt_pk_f16_f32 v31, v170, v171
	global_store_dwordx4 v[168:169], v[28:31], off offset:256

; #define LAS __attribute__((address_space(3)))
; __device__ __forceinline__ u32x4 pk8(const f32x4 v0, const f32x4 v1) { u32x4 w; w.x = pk_f16(v0[0], v0[1]); w.y = pk_f16(v0[2], v0[3]); w.z = pk_f16(v1[0], v1[1]); w.w = pk_f16(v1[2], v1[3]); return w; }
; __device__ __forceinline__ float sigmoidf_(float x) { return __builtin_amdgcn_rcpf(1.0f + __expf(-x)); }
; __device__ __forceinline__ f32x4 sig4(const f32x4 v) { return (f32x4){sigmoidf_(v[0]), sigmoidf_(v[1]), sigmoidf_(v[2]), sigmoidf_(v[3])}; }
;     __device__ __forceinline__ void operator()(const f32x4 (&acc)[2][2][4][2], const GUnit& u, int wr, int wc, int fr, int fq, LAS unsigned char*) const {
;         const int grow0 = u.pm * 256 + wr * 64 + fr, gcol0 = u.pn * 256 + wc * 32 + 8 * fq;
;         unsigned char* base = ws + B_SG; const float* bias = b_in + gcol0;
;         f32x4 bv[2][2];
;         const bool qk = u.kind != K_SG;
; #pragma unroll
;         for (int bj = 0; bj < 2; ++bj)
; #pragma unroll
;             for (int n = 0; n < 2; ++n) bv[bj][n] = *(const f32x4*)(bias + bj * 128 + 4 * n);
; #pragma unroll
;         for (int ai = 0; ai < 2; ++ai)
; #pragma unroll
;             for (int m = 0; m < 4; ++m) { unsigned char* rowp = base + (size_t)(grow0 + ai * 128 + m * 16) * 2048 + (gcol0 - 2048);
;                 if (qk) { f16* qp = (f16*)(ws + (u.kind == K_Q ? B_Q : B_K)) + (size_t)(grow0 + ai * 128 + m * 16) * 512 + (gcol0 & 511);
; #pragma unroll
;                     for (int bj = 0; bj < 2; ++bj) *(u32x4*)(qp + bj * 128) = pk8(acc[ai][bj][m][0] + bv[bj][0], acc[ai][bj][m][1] + bv[bj][1]);
;                     continue; }
; #pragma unroll
;                 for (int bj = 0; bj < 2; ++bj) { f32x4 v0 = sig4(acc[ai][bj][m][0] + bv[bj][0]) * 255.0f, v1 = sig4(acc[ai][bj][m][1] + bv[bj][1]) * 255.0f; u32x2 o = {0u, 0u};
;                     o.x = __builtin_amdgcn_cvt_pk_u8_f32(v0[0], 0, o.x); o.x = __builtin_amdgcn_cvt_pk_u8_f32(v0[1], 1, o.x); o.x = __builtin_amdgcn_cvt_pk_u8_f32(v0[2], 2, o.x); o.x = __builtin_amdgcn_cvt_pk_u8_f32(v0[3], 3, o.x);
;                     o.y = __builtin_amdgcn_cvt_pk_u8_f32(v1[0], 0, o.y); o.y = __builtin_amdgcn_cvt_pk_u8_f32(v1[1], 1, o.y); o.y = __builtin_amdgcn_cvt_pk_u8_f32(v1[2], 2, o.y); o.y = __builtin_amdgcn_cvt_pk_u8_f32(v1[3], 3, o.y);
;                     *(u32x2*)(rowp + bj * 128) = o; } }
;     }
.Lsg_mine:
	s_mov_b32 s98, 0xbfb8aa3b
	v_lshl_add_u64 v[16:17], s[54:55], 0, v[16:17]
	v_lshlrev_b64 v[28:29], 11, v[18:19]
	v_lshl_add_u64 v[28:29], v[16:17], 0, v[28:29]
	v_add_co_u32_e32 v168, vcc, s88, v28
	v_addc_co_u32_e32 v169, vcc, 0, v29, vcc
	v_pk_mul_f32 v[0:1], v[0:1], s[98:99] op_sel_hi:[1,0]
	v_pk_mul_f32 v[2:3], v[2:3], s[98:99] op_sel_hi:[1,0]
	v_pk_mul_f32 v[4:5], v[4:5], s[98:99] op_sel_hi:[1,0]
	v_pk_mul_f32 v[6:7], v[6:7], s[98:99] op_sel_hi:[1,0]
	v_pk_mul_f32 v[8:9], v[8:9], s[98:99] op_sel_hi:[1,0]
	v_pk_mul_f32 v[10:11], v[10:11], s[98:99] op_sel_hi:[1,0]
	v_pk_mul_f32 v[12:13], v[12:13], s[98:99] op_sel_hi:[1,0]
	v_pk_mul_f32 v[14:15], v[14:15], s[98:99] op_sel_hi:[1,0]
	v_pk_fma_f32 v[20:21], v[158:159], s[98:99], v[12:13] op_sel_hi:[1,0,1]
	v_pk_fma_f32 v[24:25], v[154:155], s[98:99], v[8:9] op_sel_hi:[1,0,1]
	v_pk_fma_f32 v[22:23], v[160:161], s[98:99], v[14:15] op_sel_hi:[1,0,1]
	v_pk_fma_f32 v[26:27], v[156:157], s[98:99], v[10:11] op_sel_hi:[1,0,1]
	v_exp_f32_e32 v20, v20
	v_exp_f32_e32 v24, v24
	v_exp_f32_e32 v21, v21
	v_exp_f32_e32 v25, v25
	v_exp_f32_e32 v22, v22
	v_exp_f32_e32 v26, v26
	v_exp_f32_e32 v23, v23
	v_exp_f32_e32 v27, v27
	v_pk_add_f32 v[20:21], v[20:21], 1.0 op_sel_hi:[1,0]
	v_pk_add_f32 v[24:25], v[24:25], 1.0 op_sel_hi:[1,0]
	v_pk_add_f32 v[22:23], v[22:23], 1.0 op_sel_hi:[1,0]
	v_pk_add_f32 v[26:27], v[26:27], 1.0 op_sel_hi:[1,0]
	v_rcp_f32_e32 v20, v20
	v_rcp_f32_e32 v24, v24
	v_rcp_f32_e32 v21, v21
	v_rcp_f32_e32 v25, v25
	v_rcp_f32_e32 v22, v22
	v_rcp_f32_e32 v26, v26
	v_rcp_f32_e32 v23, v23
	v_rcp_f32_e32 v27, v27
	v_pk_mul_f32 v[20:21], v[20:21], s[62:63] op_sel_hi:[1,0]
	v_pk_mul_f32 v[24:25], v[24:25], s[62:63] op_sel_hi:[1,0]
	v_pk_mul_f32 v[22:23], v[22:23], s[62:63] op_sel_hi:[1,0]
	v_pk_mul_f32 v[26:27], v[26:27], s[62:63] op_sel_hi:[1,0]
	v_cvt_pk_u8_f32 v30, v20, 0, 0
	v_cvt_pk_u8_f32 v31, v24, 0, 0
	v_cvt_pk_u8_f32 v30, v21, 1, v30
	v_cvt_pk_u8_f32 v31, v25, 1, v31
	v_cvt_pk_u8_f32 v30, v22, 2, v30
	v_cvt_pk_u8_f32 v31, v26, 2, v31
	v_cvt_pk_u8_f32 v30, v23, 3, v30
	v_cvt_pk_u8_f32 v31, v27, 3, v31
	global_store_dwordx2 v[168:169], v[30:31], off offset:2048
	v_pk_fma_f32 v[20:21], v[126:127], s[98:99], v[4:5] op_sel_hi:[1,0,1]
	v_pk_fma_f32 v[24:25], v[122:123], s[98:99], v[0:1] op_sel_hi:[1,0,1]
	v_pk_fma_f32 v[22:23], v[128:129], s[98:99], v[6:7] op_sel_hi:[1,0,1]
	v_pk_fma_f32 v[26:27], v[124:125], s[98:99], v[2:3] op_sel_hi:[1,0,1]
	v_exp_f32_e32 v20, v20
	v_exp_f32_e32 v24, v24
	v_exp_f32_e32 v21, v21
	v_exp_f32_e32 v25, v25
	v_exp_f32_e32 v22, v22
	v_exp_f32_e32 v26, v26
	v_exp_f32_e32 v23, v23
	v_exp_f32_e32 v27, v27
	v_pk_add_f32 v[20:21], v[20:21], 1.0 op_sel_hi:[1,0]
	v_pk_add_f32 v[24:25], v[24:25], 1.0 op_sel_hi:[1,0]
	v_pk_add_f32 v[22:23], v[22:23], 1.0 op_sel_hi:[1,0]
	v_pk_add_f32 v[26:27], v[26:27], 1.0 op_sel_hi:[1,0]
	v_rcp_f32_e32 v20, v20
	v_rcp_f32_e32 v24, v24
	v_rcp_f32_e32 v21, v21
	v_rcp_f32_e32 v25, v25
	v_rcp_f32_e32 v22, v22
	v_rcp_f32_e32 v26, v26
	v_rcp_f32_e32 v23, v23
	v_rcp_f32_e32 v27, v27
	v_pk_mul_f32 v[20:21], v[20:21], s[62:63] op_sel_hi:[1,0]
	v_pk_mul_f32 v[24:25], v[24:25], s[62:63] op_sel_hi:[1,0]
	v_pk_mul_f32 v[22:23], v[22:23], s[62:63] op_sel_hi:[1,0]
	v_pk_mul_f32 v[26:27], v[26:27], s[62:63] op_sel_hi:[1,0]
	v_cvt_pk_u8_f32 v28, v20, 0, 0
	v_cvt_pk_u8_f32 v29, v24, 0, 0
	v_cvt_pk_u8_f32 v28, v21, 1, v28
	v_cvt_pk_u8_f32 v29, v25, 1, v29
	v_cvt_pk_u8_f32 v28, v22, 2, v28
	v_cvt_pk_u8_f32 v29, v26, 2, v29
	v_cvt_pk_u8_f32 v28, v23, 3, v28
	v_cvt_pk_u8_f32 v29, v27, 3, v29
	global_store_dwordx2 v[168:169], v[28:29], off offset:2176
	v_add_co_u32_e32 v170, vcc, 0x8000, v168
	v_addc_co_u32_e32 v171, vcc, 0, v169, vcc
	v_pk_fma_f32 v[20:21], v[150:151], s[98:99], v[12:13] op_sel_hi:[1,0,1]
	v_pk_fma_f32 v[24:25], v[146:147], s[98:99], v[8:9] op_sel_hi:[1,0,1]
	v_pk_fma_f32 v[22:23], v[152:153], s[98:99], v[14:15] op_sel_hi:[1,0,1]
	v_pk_fma_f32 v[26:27], v[148:149], s[98:99], v[10:11] op_sel_hi:[1,0,1]
	v_exp_f32_e32 v20, v20
	v_exp_f32_e32 v24, v24
	v_exp_f32_e32 v21, v21
	v_exp_f32_e32 v25, v25
	v_exp_f32_e32 v22, v22
	v_exp_f32_e32 v26, v26
	v_exp_f32_e32 v23, v23
	v_exp_f32_e32 v27, v27
	v_pk_add_f32 v[20:21], v[20:21], 1.0 op_sel_hi:[1,0]
	v_pk_add_f32 v[24:25], v[24:25], 1.0 op_sel_hi:[1,0]
	v_pk_add_f32 v[22:23], v[22:23], 1.0 op_sel_hi:[1,0]
	v_pk_add_f32 v[26:27], v[26:27], 1.0 op_sel_hi:[1,0]
	v_rcp_f32_e32 v20, v20
	v_rcp_f32_e32 v24, v24
	v_rcp_f32_e32 v21, v21
	v_rcp_f32_e32 v25, v25
	v_rcp_f32_e32 v22, v22
	v_rcp_f32_e32 v26, v26
	v_rcp_f32_e32 v23, v23
	v_rcp_f32_e32 v27, v27
	v_pk_mul_f32 v[20:21], v[20:21], s[62:63] op_sel_hi:[1,0]
	v_pk_mul_f32 v[24:25], v[24:25], s[62:63] op_sel_hi:[1,0]
	v_pk_mul_f32 v[22:23], v[22:23], s[62:63] op_sel_hi:[1,0]
	v_pk_mul_f32 v[26:27], v[26:27], s[62:63] op_sel_hi:[1,0]
	v_cvt_pk_u8_f32 v30, v20, 0, 0
	v_cvt_pk_u8_f32 v31, v24, 0, 0
	v_cvt_pk_u8_f32 v30, v21, 1, v30
	v_cvt_pk_u8_f32 v31, v25, 1, v31
	v_cvt_pk_u8_f32 v30, v22, 2, v30
	v_cvt_pk_u8_f32 v31, v26, 2, v31
	v_cvt_pk_u8_f32 v30, v23, 3, v30
	v_cvt_pk_u8_f32 v31, v27, 3, v31
	global_store_dwordx2 v[170:171], v[30:31], off offset:2048
	v_pk_fma_f32 v[20:21], v[118:119], s[98:99], v[4:5] op_sel_hi:[1,0,1]
	v_pk_fma_f32 v[24:25], v[114:115], s[98:99], v[0:1] op_sel_hi:[1,0,1]
	v_pk_fma_f32 v[22:23], v[120:121], s[98:99], v[6:7] op_sel_hi:[1,0,1]
	v_pk_fma_f32 v[26:27], v[116:117], s[98:99], v[2:3] op_sel_hi:[1,0,1]
	v_exp_f32_e32 v20, v20
	v_exp_f32_e32 v24, v24
	v_exp_f32_e32 v21, v21
	v_exp_f32_e32 v25, v25
	v_exp_f32_e32 v22, v22
	v_exp_f32_e32 v26, v26
	v_exp_f32_e32 v23, v23
	v_exp_f32_e32 v27, v27
; #define LAS __attribute__((address_space(3)))
; __device__ __forceinline__ u32x4 pk8(const f32x4 v0, const f32x4 v1) { u32x4 w; w.x = pk_f16(v0[0], v0[1]); w.y = pk_f16(v0[2], v0[3]); w.z = pk_f16(v1[0], v1[1]); w.w = pk_f16(v1[2], v1[3]); return w; }
; __device__ __forceinline__ float sigmoidf_(float x) { return __builtin_amdgcn_rcpf(1.0f + __expf(-x)); }
; __device__ __forceinline__ f32x4 sig4(const f32x4 v) { return (f32x4){sigmoidf_(v[0]), sigmoidf_(v[1]), sigmoidf_(v[2]), sigmoidf_(v[3])}; }
;     __device__ __forceinline__ void operator()(const f32x4 (&acc)[2][2][4][2], const GUnit& u, int wr, int wc, int fr, int fq, LAS unsigned char*) const {
;         const int grow0 = u.pm * 256 + wr * 64 + fr, gcol0 = u.pn * 256 + wc * 32 + 8 * fq;
;         unsigned char* base = ws + B_SG; const float* bias = b_in + gcol0;
;         f32x4 bv[2][2];
;         const bool qk = u.kind != K_SG;
; #pragma unroll
;         for (int bj = 0; bj < 2; ++bj)
; #pragma unroll
;             for (int n = 0; n < 2; ++n) bv[bj][n] = *(const f32x4*)(bias + bj * 128 + 4 * n);
; #pragma unroll
;         for (int ai = 0; ai < 2; ++ai)
; #pragma unroll
;             for (int m = 0; m < 4; ++m) { unsigned char* rowp = base + (size_t)(grow0 + ai * 128 + m * 16) * 2048 + (gcol0 - 2048);
;                 if (qk) { f16* qp = (f16*)(ws + (u.kind == K_Q ? B_Q : B_K)) + (size_t)(grow0 + ai * 128 + m * 16) * 512 + (gcol0 & 511);
; #pragma unroll
;                     for (int bj = 0; bj < 2; ++bj) *(u32x4*)(qp + bj * 128) = pk8(acc[ai][bj][m][0] + bv[bj][0], acc[ai][bj][m][1] + bv[bj][1]);
;                     continue; }
; #pragma unroll
;                 for (int bj = 0; bj < 2; ++bj) { f32x4 v0 = sig4(acc[ai][bj][m][0] + bv[bj][0]) * 255.0f, v1 = sig4(acc[ai][bj][m][1] + bv[bj][1]) * 255.0f; u32x2 o = {0u, 0u};
;                     o.x = __builtin_amdgcn_cvt_pk_u8_f32(v0[0], 0, o.x); o.x = __builtin_amdgcn_cvt_pk_u8_f32(v0[1], 1, o.x); o.x = __builtin_amdgcn_cvt_pk_u8_f32(v0[2], 2, o.x); o.x = __builtin_amdgcn_cvt_pk_u8_f32(v0[3], 3, o.x);
;                     o.y = __builtin_amdgcn_cvt_pk_u8_f32(v1[0], 0, o.y); o.y = __builtin_amdgcn_cvt_pk_u8_f32(v1[1], 1, o.y); o.y = __builtin_amdgcn_cvt_pk_u8_f32(v1[2], 2, o.y); o.y = __builtin_amdgcn_cvt_pk_u8_f32(v1[3], 3, o.y);
;                     *(u32x2*)(rowp + bj * 128) = o; } }
;     }
	v_pk_add_f32 v[20:21], v[20:21], 1.0 op_sel_hi:[1,0]
	v_pk_add_f32 v[24:25], v[24:25], 1.0 op_sel_hi:[1,0]
	v_pk_add_f32 v[22:23], v[22:23], 1.0 op_sel_hi:[1,0]
	v_pk_add_f32 v[26:27], v[26:27], 1.0 op_sel_hi:[1,0]
	v_rcp_f32_e32 v20, v20
	v_rcp_f32_e32 v24, v24
	v_rcp_f32_e32 v21, v21
	v_rcp_f32_e32 v25, v25
	v_rcp_f32_e32 v22, v22
	v_rcp_f32_e32 v26, v26
	v_rcp_f32_e32 v23, v23
	v_rcp_f32_e32 v27, v27
	v_pk_mul_f32 v[20:21], v[20:21], s[62:63] op_sel_hi:[1,0]
	v_pk_mul_f32 v[24:25], v[24:25], s[62:63] op_sel_hi:[1,0]
	v_pk_mul_f32 v[22:23], v[22:23], s[62:63] op_sel_hi:[1,0]
	v_pk_mul_f32 v[26:27], v[26:27], s[62:63] op_sel_hi:[1,0]
	v_cvt_pk_u8_f32 v28, v20, 0, 0
	v_cvt_pk_u8_f32 v29, v24, 0, 0
	v_cvt_pk_u8_f32 v28, v21, 1, v28
	v_cvt_pk_u8_f32 v29, v25, 1, v29
	v_cvt_pk_u8_f32 v28, v22, 2, v28
	v_cvt_pk_u8_f32 v29, v26, 2, v29
	v_cvt_pk_u8_f32 v28, v23, 3, v28
	v_cvt_pk_u8_f32 v29, v27, 3, v29
	global_store_dwordx2 v[170:171], v[28:29], off offset:2176
	v_add_co_u32_e32 v170, vcc, 0x10000, v168
	v_addc_co_u32_e32 v171, vcc, 0, v169, vcc
	v_pk_fma_f32 v[20:21], v[142:143], s[98:99], v[12:13] op_sel_hi:[1,0,1]
	v_pk_fma_f32 v[24:25], v[138:139], s[98:99], v[8:9] op_sel_hi:[1,0,1]
	v_pk_fma_f32 v[22:23], v[144:145], s[98:99], v[14:15] op_sel_hi:[1,0,1]
	v_pk_fma_f32 v[26:27], v[140:141], s[98:99], v[10:11] op_sel_hi:[1,0,1]
	v_exp_f32_e32 v20, v20
	v_exp_f32_e32 v24, v24
	v_exp_f32_e32 v21, v21
	v_exp_f32_e32 v25, v25
	v_exp_f32_e32 v22, v22
	v_exp_f32_e32 v26, v26
	v_exp_f32_e32 v23, v23
	v_exp_f32_e32 v27, v27
	v_pk_add_f32 v[20:21], v[20:21], 1.0 op_sel_hi:[1,0]
	v_pk_add_f32 v[24:25], v[24:25], 1.0 op_sel_hi:[1,0]
	v_pk_add_f32 v[22:23], v[22:23], 1.0 op_sel_hi:[1,0]
	v_pk_add_f32 v[26:27], v[26:27], 1.0 op_sel_hi:[1,0]
	v_rcp_f32_e32 v20, v20
	v_rcp_f32_e32 v24, v24
	v_rcp_f32_e32 v21, v21
	v_rcp_f32_e32 v25, v25
	v_rcp_f32_e32 v22, v22
	v_rcp_f32_e32 v26, v26
	v_rcp_f32_e32 v23, v23
	v_rcp_f32_e32 v27, v27
	v_pk_mul_f32 v[20:21], v[20:21], s[62:63] op_sel_hi:[1,0]
	v_pk_mul_f32 v[24:25], v[24:25], s[62:63] op_sel_hi:[1,0]
	v_pk_mul_f32 v[22:23], v[22:23], s[62:63] op_sel_hi:[1,0]
	v_pk_mul_f32 v[26:27], v[26:27], s[62:63] op_sel_hi:[1,0]
	v_cvt_pk_u8_f32 v30, v20, 0, 0
	v_cvt_pk_u8_f32 v31, v24, 0, 0
	v_cvt_pk_u8_f32 v30, v21, 1, v30
	v_cvt_pk_u8_f32 v31, v25, 1, v31
	v_cvt_pk_u8_f32 v30, v22, 2, v30
	v_cvt_pk_u8_f32 v31, v26, 2, v31
	v_cvt_pk_u8_f32 v30, v23, 3, v30
	v_cvt_pk_u8_f32 v31, v27, 3, v31
	global_store_dwordx2 v[170:171], v[30:31], off offset:2048
	v_pk_fma_f32 v[20:21], v[110:111], s[98:99], v[4:5] op_sel_hi:[1,0,1]
	v_pk_fma_f32 v[24:25], v[106:107], s[98:99], v[0:1] op_sel_hi:[1,0,1]
	v_pk_fma_f32 v[22:23], v[112:113], s[98:99], v[6:7] op_sel_hi:[1,0,1]
	v_pk_fma_f32 v[26:27], v[108:109], s[98:99], v[2:3] op_sel_hi:[1,0,1]
	v_exp_f32_e32 v20, v20
	v_exp_f32_e32 v24, v24
	v_exp_f32_e32 v21, v21
	v_exp_f32_e32 v25, v25
	v_exp_f32_e32 v22, v22
	v_exp_f32_e32 v26, v26
	v_exp_f32_e32 v23, v23
	v_exp_f32_e32 v27, v27
	v_pk_add_f32 v[20:21], v[20:21], 1.0 op_sel_hi:[1,0]
	v_pk_add_f32 v[24:25], v[24:25], 1.0 op_sel_hi:[1,0]
	v_pk_add_f32 v[22:23], v[22:23], 1.0 op_sel_hi:[1,0]
	v_pk_add_f32 v[26:27], v[26:27], 1.0 op_sel_hi:[1,0]
	v_rcp_f32_e32 v20, v20
	v_rcp_f32_e32 v24, v24
	v_rcp_f32_e32 v21, v21
	v_rcp_f32_e32 v25, v25
	v_rcp_f32_e32 v22, v22
	v_rcp_f32_e32 v26, v26
	v_rcp_f32_e32 v23, v23
	v_rcp_f32_e32 v27, v27
	v_pk_mul_f32 v[20:21], v[20:21], s[62:63] op_sel_hi:[1,0]
	v_pk_mul_f32 v[24:25], v[24:25], s[62:63] op_sel_hi:[1,0]
	v_pk_mul_f32 v[22:23], v[22:23], s[62:63] op_sel_hi:[1,0]
	v_pk_mul_f32 v[26:27], v[26:27], s[62:63] op_sel_hi:[1,0]
	v_cvt_pk_u8_f32 v28, v20, 0, 0
	v_cvt_pk_u8_f32 v29, v24, 0, 0
	v_cvt_pk_u8_f32 v28, v21, 1, v28
	v_cvt_pk_u8_f32 v29, v25, 1, v29
	v_cvt_pk_u8_f32 v28, v22, 2, v28
	v_cvt_pk_u8_f32 v29, v26, 2, v29
	v_cvt_pk_u8_f32 v28, v23, 3, v28
	v_cvt_pk_u8_f32 v29, v27, 3, v29
	global_store_dwordx2 v[170:171], v[28:29], off offset:2176
	v_add_co_u32_e32 v170, vcc, 0x18000, v168
	v_addc_co_u32_e32 v171, vcc, 0, v169, vcc
	v_pk_fma_f32 v[20:21], v[134:135], s[98:99], v[12:13] op_sel_hi:[1,0,1]
	v_pk_fma_f32 v[24:25], v[130:131], s[98:99], v[8:9] op_sel_hi:[1,0,1]
	v_pk_fma_f32 v[22:23], v[136:137], s[98:99], v[14:15] op_sel_hi:[1,0,1]
	v_pk_fma_f32 v[26:27], v[132:133], s[98:99], v[10:11] op_sel_hi:[1,0,1]
	v_exp_f32_e32 v20, v20
	v_exp_f32_e32 v24, v24
	v_exp_f32_e32 v21, v21
	v_exp_f32_e32 v25, v25
	v_exp_f32_e32 v22, v22
	v_exp_f32_e32 v26, v26
	v_exp_f32_e32 v23, v23
	v_exp_f32_e32 v27, v27
	v_pk_add_f32 v[20:21], v[20:21], 1.0 op_sel_hi:[1,0]
	v_pk_add_f32 v[24:25], v[24:25], 1.0 op_sel_hi:[1,0]
	v_pk_add_f32 v[22:23], v[22:23], 1.0 op_sel_hi:[1,0]
	v_pk_add_f32 v[26:27], v[26:27], 1.0 op_sel_hi:[1,0]
	v_rcp_f32_e32 v20, v20
	v_rcp_f32_e32 v24, v24
	v_rcp_f32_e32 v21, v21
	v_rcp_f32_e32 v25, v25
	v_rcp_f32_e32 v22, v22
	v_rcp_f32_e32 v26, v26
	v_rcp_f32_e32 v23, v23
	v_rcp_f32_e32 v27, v27
	v_pk_mul_f32 v[20:21], v[20:21], s[62:63] op_sel_hi:[1,0]
	v_pk_mul_f32 v[24:25], v[24:25], s[62:63] op_sel_hi:[1,0]
	v_pk_mul_f32 v[22:23], v[22:23], s[62:63] op_sel_hi:[1,0]
	v_pk_mul_f32 v[26:27], v[26:27], s[62:63] op_sel_hi:[1,0]
	v_cvt_pk_u8_f32 v30, v20, 0, 0
	v_cvt_pk_u8_f32 v31, v24, 0, 0
	v_cvt_pk_u8_f32 v30, v21, 1, v30
	v_cvt_pk_u8_f32 v31, v25, 1, v31
	v_cvt_pk_u8_f32 v30, v22, 2, v30
	v_cvt_pk_u8_f32 v31, v26, 2, v31
	v_cvt_pk_u8_f32 v30, v23, 3, v30
	v_cvt_pk_u8_f32 v31, v27, 3, v31
	global_store_dwordx2 v[170:171], v[30:31], off offset:2048
	v_pk_fma_f32 v[20:21], v[102:103], s[98:99], v[4:5] op_sel_hi:[1,0,1]
	v_pk_fma_f32 v[24:25], v[98:99], s[98:99], v[0:1] op_sel_hi:[1,0,1]
; #define LAS __attribute__((address_space(3)))
; __device__ __forceinline__ u32x4 pk8(const f32x4 v0, const f32x4 v1) { u32x4 w; w.x = pk_f16(v0[0], v0[1]); w.y = pk_f16(v0[2], v0[3]); w.z = pk_f16(v1[0], v1[1]); w.w = pk_f16(v1[2], v1[3]); return w; }
; __device__ __forceinline__ float sigmoidf_(float x) { return __builtin_amdgcn_rcpf(1.0f + __expf(-x)); }
; __device__ __forceinline__ f32x4 sig4(const f32x4 v) { return (f32x4){sigmoidf_(v[0]), sigmoidf_(v[1]), sigmoidf_(v[2]), sigmoidf_(v[3])}; }
;     __device__ __forceinline__ void operator()(const f32x4 (&acc)[2][2][4][2], const GUnit& u, int wr, int wc, int fr, int fq, LAS unsigned char*) const {
;         const int grow0 = u.pm * 256 + wr * 64 + fr, gcol0 = u.pn * 256 + wc * 32 + 8 * fq;
;         unsigned char* base = ws + B_SG; const float* bias = b_in + gcol0;
;         f32x4 bv[2][2];
;         const bool qk = u.kind != K_SG;
; #pragma unroll
;         for (int bj = 0; bj < 2; ++bj)
; #pragma unroll
;             for (int n = 0; n < 2; ++n) bv[bj][n] = *(const f32x4*)(bias + bj * 128 + 4 * n);
; #pragma unroll
;         for (int ai = 0; ai < 2; ++ai)
; #pragma unroll
;             for (int m = 0; m < 4; ++m) { unsigned char* rowp = base + (size_t)(grow0 + ai * 128 + m * 16) * 2048 + (gcol0 - 2048);
;                 if (qk) { f16* qp = (f16*)(ws + (u.kind == K_Q ? B_Q : B_K)) + (size_t)(grow0 + ai * 128 + m * 16) * 512 + (gcol0 & 511);
; #pragma unroll
;                     for (int bj = 0; bj < 2; ++bj) *(u32x4*)(qp + bj * 128) = pk8(acc[ai][bj][m][0] + bv[bj][0], acc[ai][bj][m][1] + bv[bj][1]);
;                     continue; }
; #pragma unroll
;                 for (int bj = 0; bj < 2; ++bj) { f32x4 v0 = sig4(acc[ai][bj][m][0] + bv[bj][0]) * 255.0f, v1 = sig4(acc[ai][bj][m][1] + bv[bj][1]) * 255.0f; u32x2 o = {0u, 0u};
;                     o.x = __builtin_amdgcn_cvt_pk_u8_f32(v0[0], 0, o.x); o.x = __builtin_amdgcn_cvt_pk_u8_f32(v0[1], 1, o.x); o.x = __builtin_amdgcn_cvt_pk_u8_f32(v0[2], 2, o.x); o.x = __builtin_amdgcn_cvt_pk_u8_f32(v0[3], 3, o.x);
;                     o.y = __builtin_amdgcn_cvt_pk_u8_f32(v1[0], 0, o.y); o.y = __builtin_amdgcn_cvt_pk_u8_f32(v1[1], 1, o.y); o.y = __builtin_amdgcn_cvt_pk_u8_f32(v1[2], 2, o.y); o.y = __builtin_amdgcn_cvt_pk_u8_f32(v1[3], 3, o.y);
;                     *(u32x2*)(rowp + bj * 128) = o; } }
;     }
	v_pk_fma_f32 v[22:23], v[104:105], s[98:99], v[6:7] op_sel_hi:[1,0,1]
	v_pk_fma_f32 v[26:27], v[100:101], s[98:99], v[2:3] op_sel_hi:[1,0,1]
	v_exp_f32_e32 v20, v20
	v_exp_f32_e32 v24, v24
	v_exp_f32_e32 v21, v21
	v_exp_f32_e32 v25, v25
	v_exp_f32_e32 v22, v22
	v_exp_f32_e32 v26, v26
	v_exp_f32_e32 v23, v23
	v_exp_f32_e32 v27, v27
	v_pk_add_f32 v[20:21], v[20:21], 1.0 op_sel_hi:[1,0]
	v_pk_add_f32 v[24:25], v[24:25], 1.0 op_sel_hi:[1,0]
	v_pk_add_f32 v[22:23], v[22:23], 1.0 op_sel_hi:[1,0]
	v_pk_add_f32 v[26:27], v[26:27], 1.0 op_sel_hi:[1,0]
	v_rcp_f32_e32 v20, v20
	v_rcp_f32_e32 v24, v24
	v_rcp_f32_e32 v21, v21
	v_rcp_f32_e32 v25, v25
	v_rcp_f32_e32 v22, v22
	v_rcp_f32_e32 v26, v26
	v_rcp_f32_e32 v23, v23
	v_rcp_f32_e32 v27, v27
	v_pk_mul_f32 v[20:21], v[20:21], s[62:63] op_sel_hi:[1,0]
	v_pk_mul_f32 v[24:25], v[24:25], s[62:63] op_sel_hi:[1,0]
	v_pk_mul_f32 v[22:23], v[22:23], s[62:63] op_sel_hi:[1,0]
	v_pk_mul_f32 v[26:27], v[26:27], s[62:63] op_sel_hi:[1,0]
	v_cvt_pk_u8_f32 v28, v20, 0, 0
	v_cvt_pk_u8_f32 v29, v24, 0, 0
	v_cvt_pk_u8_f32 v28, v21, 1, v28
	v_cvt_pk_u8_f32 v29, v25, 1, v29
	v_cvt_pk_u8_f32 v28, v22, 2, v28
	v_cvt_pk_u8_f32 v29, v26, 2, v29
	v_cvt_pk_u8_f32 v28, v23, 3, v28
	v_cvt_pk_u8_f32 v29, v27, 3, v29
	global_store_dwordx2 v[170:171], v[28:29], off offset:2176
	v_add_co_u32_e32 v170, vcc, 0x40000, v168
	v_addc_co_u32_e32 v171, vcc, 0, v169, vcc
	v_pk_fma_f32 v[20:21], v[94:95], s[98:99], v[12:13] op_sel_hi:[1,0,1]
	v_pk_fma_f32 v[24:25], v[90:91], s[98:99], v[8:9] op_sel_hi:[1,0,1]
	v_pk_fma_f32 v[22:23], v[96:97], s[98:99], v[14:15] op_sel_hi:[1,0,1]
	v_pk_fma_f32 v[26:27], v[92:93], s[98:99], v[10:11] op_sel_hi:[1,0,1]
	v_exp_f32_e32 v20, v20
	v_exp_f32_e32 v24, v24
	v_exp_f32_e32 v21, v21
	v_exp_f32_e32 v25, v25
	v_exp_f32_e32 v22, v22
	v_exp_f32_e32 v26, v26
	v_exp_f32_e32 v23, v23
	v_exp_f32_e32 v27, v27
	v_pk_add_f32 v[20:21], v[20:21], 1.0 op_sel_hi:[1,0]
	v_pk_add_f32 v[24:25], v[24:25], 1.0 op_sel_hi:[1,0]
	v_pk_add_f32 v[22:23], v[22:23], 1.0 op_sel_hi:[1,0]
	v_pk_add_f32 v[26:27], v[26:27], 1.0 op_sel_hi:[1,0]
	v_rcp_f32_e32 v20, v20
	v_rcp_f32_e32 v24, v24
	v_rcp_f32_e32 v21, v21
	v_rcp_f32_e32 v25, v25
	v_rcp_f32_e32 v22, v22
	v_rcp_f32_e32 v26, v26
	v_rcp_f32_e32 v23, v23
	v_rcp_f32_e32 v27, v27
	v_pk_mul_f32 v[20:21], v[20:21], s[62:63] op_sel_hi:[1,0]
	v_pk_mul_f32 v[24:25], v[24:25], s[62:63] op_sel_hi:[1,0]
	v_pk_mul_f32 v[22:23], v[22:23], s[62:63] op_sel_hi:[1,0]
	v_pk_mul_f32 v[26:27], v[26:27], s[62:63] op_sel_hi:[1,0]
	v_cvt_pk_u8_f32 v30, v20, 0, 0
	v_cvt_pk_u8_f32 v31, v24, 0, 0
	v_cvt_pk_u8_f32 v30, v21, 1, v30
	v_cvt_pk_u8_f32 v31, v25, 1, v31
	v_cvt_pk_u8_f32 v30, v22, 2, v30
	v_cvt_pk_u8_f32 v31, v26, 2, v31
	v_cvt_pk_u8_f32 v30, v23, 3, v30
	v_cvt_pk_u8_f32 v31, v27, 3, v31
	global_store_dwordx2 v[170:171], v[30:31], off offset:2048
	v_pk_fma_f32 v[20:21], v[62:63], s[98:99], v[4:5] op_sel_hi:[1,0,1]
	v_pk_fma_f32 v[24:25], v[58:59], s[98:99], v[0:1] op_sel_hi:[1,0,1]
	v_pk_fma_f32 v[22:23], v[64:65], s[98:99], v[6:7] op_sel_hi:[1,0,1]
	v_pk_fma_f32 v[26:27], v[60:61], s[98:99], v[2:3] op_sel_hi:[1,0,1]
	v_exp_f32_e32 v20, v20
	v_exp_f32_e32 v24, v24
	v_exp_f32_e32 v21, v21
	v_exp_f32_e32 v25, v25
	v_exp_f32_e32 v22, v22
	v_exp_f32_e32 v26, v26
	v_exp_f32_e32 v23, v23
	v_exp_f32_e32 v27, v27
	v_pk_add_f32 v[20:21], v[20:21], 1.0 op_sel_hi:[1,0]
	v_pk_add_f32 v[24:25], v[24:25], 1.0 op_sel_hi:[1,0]
	v_pk_add_f32 v[22:23], v[22:23], 1.0 op_sel_hi:[1,0]
	v_pk_add_f32 v[26:27], v[26:27], 1.0 op_sel_hi:[1,0]
	v_rcp_f32_e32 v20, v20
	v_rcp_f32_e32 v24, v24
	v_rcp_f32_e32 v21, v21
	v_rcp_f32_e32 v25, v25
	v_rcp_f32_e32 v22, v22
	v_rcp_f32_e32 v26, v26
	v_rcp_f32_e32 v23, v23
	v_rcp_f32_e32 v27, v27
	v_pk_mul_f32 v[20:21], v[20:21], s[62:63] op_sel_hi:[1,0]
	v_pk_mul_f32 v[24:25], v[24:25], s[62:63] op_sel_hi:[1,0]
	v_pk_mul_f32 v[22:23], v[22:23], s[62:63] op_sel_hi:[1,0]
	v_pk_mul_f32 v[26:27], v[26:27], s[62:63] op_sel_hi:[1,0]
	v_cvt_pk_u8_f32 v28, v20, 0, 0
	v_cvt_pk_u8_f32 v29, v24, 0, 0
	v_cvt_pk_u8_f32 v28, v21, 1, v28
	v_cvt_pk_u8_f32 v29, v25, 1, v29
	v_cvt_pk_u8_f32 v28, v22, 2, v28
	v_cvt_pk_u8_f32 v29, v26, 2, v29
	v_cvt_pk_u8_f32 v28, v23, 3, v28
	v_cvt_pk_u8_f32 v29, v27, 3, v29
	global_store_dwordx2 v[170:171], v[28:29], off offset:2176
	v_add_co_u32_e32 v170, vcc, 0x48000, v168
	v_addc_co_u32_e32 v171, vcc, 0, v169, vcc
	v_pk_fma_f32 v[20:21], v[86:87], s[98:99], v[12:13] op_sel_hi:[1,0,1]
	v_pk_fma_f32 v[24:25], v[82:83], s[98:99], v[8:9] op_sel_hi:[1,0,1]
	v_pk_fma_f32 v[22:23], v[88:89], s[98:99], v[14:15] op_sel_hi:[1,0,1]
	v_pk_fma_f32 v[26:27], v[84:85], s[98:99], v[10:11] op_sel_hi:[1,0,1]
	v_exp_f32_e32 v20, v20
	v_exp_f32_e32 v24, v24
	v_exp_f32_e32 v21, v21
	v_exp_f32_e32 v25, v25
	v_exp_f32_e32 v22, v22
	v_exp_f32_e32 v26, v26
	v_exp_f32_e32 v23, v23
	v_exp_f32_e32 v27, v27
	v_pk_add_f32 v[20:21], v[20:21], 1.0 op_sel_hi:[1,0]
	v_pk_add_f32 v[24:25], v[24:25], 1.0 op_sel_hi:[1,0]
	v_pk_add_f32 v[22:23], v[22:23], 1.0 op_sel_hi:[1,0]
	v_pk_add_f32 v[26:27], v[26:27], 1.0 op_sel_hi:[1,0]
	v_rcp_f32_e32 v20, v20
	v_rcp_f32_e32 v24, v24
	v_rcp_f32_e32 v21, v21
	v_rcp_f32_e32 v25, v25
	v_rcp_f32_e32 v22, v22
	v_rcp_f32_e32 v26, v26
	v_rcp_f32_e32 v23, v23
	v_rcp_f32_e32 v27, v27
	v_pk_mul_f32 v[20:21], v[20:21], s[62:63] op_sel_hi:[1,0]
	v_pk_mul_f32 v[24:25], v[24:25], s[62:63] op_sel_hi:[1,0]
	v_pk_mul_f32 v[22:23], v[22:23], s[62:63] op_sel_hi:[1,0]
	v_pk_mul_f32 v[26:27], v[26:27], s[62:63] op_sel_hi:[1,0]
	v_cvt_pk_u8_f32 v30, v20, 0, 0
	v_cvt_pk_u8_f32 v31, v24, 0, 0
	v_cvt_pk_u8_f32 v30, v21, 1, v30
	v_cvt_pk_u8_f32 v31, v25, 1, v31
	v_cvt_pk_u8_f32 v30, v22, 2, v30
; #define LAS __attribute__((address_space(3)))
; __device__ __forceinline__ u32x4 pk8(const f32x4 v0, const f32x4 v1) { u32x4 w; w.x = pk_f16(v0[0], v0[1]); w.y = pk_f16(v0[2], v0[3]); w.z = pk_f16(v1[0], v1[1]); w.w = pk_f16(v1[2], v1[3]); return w; }
; __device__ __forceinline__ float sigmoidf_(float x) { return __builtin_amdgcn_rcpf(1.0f + __expf(-x)); }
; __device__ __forceinline__ f32x4 sig4(const f32x4 v) { return (f32x4){sigmoidf_(v[0]), sigmoidf_(v[1]), sigmoidf_(v[2]), sigmoidf_(v[3])}; }
;     __device__ __forceinline__ void operator()(const f32x4 (&acc)[2][2][4][2], const GUnit& u, int wr, int wc, int fr, int fq, LAS unsigned char*) const {
;         const int grow0 = u.pm * 256 + wr * 64 + fr, gcol0 = u.pn * 256 + wc * 32 + 8 * fq;
;         unsigned char* base = ws + B_SG; const float* bias = b_in + gcol0;
;         f32x4 bv[2][2];
;         const bool qk = u.kind != K_SG;
; #pragma unroll
;         for (int bj = 0; bj < 2; ++bj)
; #pragma unroll
;             for (int n = 0; n < 2; ++n) bv[bj][n] = *(const f32x4*)(bias + bj * 128 + 4 * n);
; #pragma unroll
;         for (int ai = 0; ai < 2; ++ai)
; #pragma unroll
;             for (int m = 0; m < 4; ++m) { unsigned char* rowp = base + (size_t)(grow0 + ai * 128 + m * 16) * 2048 + (gcol0 - 2048);
;                 if (qk) { f16* qp = (f16*)(ws + (u.kind == K_Q ? B_Q : B_K)) + (size_t)(grow0 + ai * 128 + m * 16) * 512 + (gcol0 & 511);
; #pragma unroll
;                     for (int bj = 0; bj < 2; ++bj) *(u32x4*)(qp + bj * 128) = pk8(acc[ai][bj][m][0] + bv[bj][0], acc[ai][bj][m][1] + bv[bj][1]);
;                     continue; }
; #pragma unroll
;                 for (int bj = 0; bj < 2; ++bj) { f32x4 v0 = sig4(acc[ai][bj][m][0] + bv[bj][0]) * 255.0f, v1 = sig4(acc[ai][bj][m][1] + bv[bj][1]) * 255.0f; u32x2 o = {0u, 0u};
;                     o.x = __builtin_amdgcn_cvt_pk_u8_f32(v0[0], 0, o.x); o.x = __builtin_amdgcn_cvt_pk_u8_f32(v0[1], 1, o.x); o.x = __builtin_amdgcn_cvt_pk_u8_f32(v0[2], 2, o.x); o.x = __builtin_amdgcn_cvt_pk_u8_f32(v0[3], 3, o.x);
;                     o.y = __builtin_amdgcn_cvt_pk_u8_f32(v1[0], 0, o.y); o.y = __builtin_amdgcn_cvt_pk_u8_f32(v1[1], 1, o.y); o.y = __builtin_amdgcn_cvt_pk_u8_f32(v1[2], 2, o.y); o.y = __builtin_amdgcn_cvt_pk_u8_f32(v1[3], 3, o.y);
;                     *(u32x2*)(rowp + bj * 128) = o; } }
;     }
	v_cvt_pk_u8_f32 v31, v26, 2, v31
	v_cvt_pk_u8_f32 v30, v23, 3, v30
	v_cvt_pk_u8_f32 v31, v27, 3, v31
	global_store_dwordx2 v[170:171], v[30:31], off offset:2048
	v_pk_fma_f32 v[20:21], v[54:55], s[98:99], v[4:5] op_sel_hi:[1,0,1]
	v_pk_fma_f32 v[24:25], v[50:51], s[98:99], v[0:1] op_sel_hi:[1,0,1]
	v_pk_fma_f32 v[22:23], v[56:57], s[98:99], v[6:7] op_sel_hi:[1,0,1]
	v_pk_fma_f32 v[26:27], v[52:53], s[98:99], v[2:3] op_sel_hi:[1,0,1]
	v_exp_f32_e32 v20, v20
	v_exp_f32_e32 v24, v24
	v_exp_f32_e32 v21, v21
	v_exp_f32_e32 v25, v25
	v_exp_f32_e32 v22, v22
	v_exp_f32_e32 v26, v26
	v_exp_f32_e32 v23, v23
	v_exp_f32_e32 v27, v27
	v_pk_add_f32 v[20:21], v[20:21], 1.0 op_sel_hi:[1,0]
	v_pk_add_f32 v[24:25], v[24:25], 1.0 op_sel_hi:[1,0]
	v_pk_add_f32 v[22:23], v[22:23], 1.0 op_sel_hi:[1,0]
	v_pk_add_f32 v[26:27], v[26:27], 1.0 op_sel_hi:[1,0]
	v_rcp_f32_e32 v20, v20
	v_rcp_f32_e32 v24, v24
	v_rcp_f32_e32 v21, v21
	v_rcp_f32_e32 v25, v25
	v_rcp_f32_e32 v22, v22
	v_rcp_f32_e32 v26, v26
	v_rcp_f32_e32 v23, v23
	v_rcp_f32_e32 v27, v27
	v_pk_mul_f32 v[20:21], v[20:21], s[62:63] op_sel_hi:[1,0]
	v_pk_mul_f32 v[24:25], v[24:25], s[62:63] op_sel_hi:[1,0]
	v_pk_mul_f32 v[22:23], v[22:23], s[62:63] op_sel_hi:[1,0]
	v_pk_mul_f32 v[26:27], v[26:27], s[62:63] op_sel_hi:[1,0]
	v_cvt_pk_u8_f32 v28, v20, 0, 0
	v_cvt_pk_u8_f32 v29, v24, 0, 0
	v_cvt_pk_u8_f32 v28, v21, 1, v28
	v_cvt_pk_u8_f32 v29, v25, 1, v29
	v_cvt_pk_u8_f32 v28, v22, 2, v28
	v_cvt_pk_u8_f32 v29, v26, 2, v29
	v_cvt_pk_u8_f32 v28, v23, 3, v28
	v_cvt_pk_u8_f32 v29, v27, 3, v29
	global_store_dwordx2 v[170:171], v[28:29], off offset:2176
	v_add_co_u32_e32 v170, vcc, 0x50000, v168
	v_addc_co_u32_e32 v171, vcc, 0, v169, vcc
	v_pk_fma_f32 v[20:21], v[78:79], s[98:99], v[12:13] op_sel_hi:[1,0,1]
	v_pk_fma_f32 v[24:25], v[74:75], s[98:99], v[8:9] op_sel_hi:[1,0,1]
	v_pk_fma_f32 v[22:23], v[80:81], s[98:99], v[14:15] op_sel_hi:[1,0,1]
	v_pk_fma_f32 v[26:27], v[76:77], s[98:99], v[10:11] op_sel_hi:[1,0,1]
	v_exp_f32_e32 v20, v20
	v_exp_f32_e32 v24, v24
	v_exp_f32_e32 v21, v21
	v_exp_f32_e32 v25, v25
	v_exp_f32_e32 v22, v22
	v_exp_f32_e32 v26, v26
	v_exp_f32_e32 v23, v23
	v_exp_f32_e32 v27, v27
	v_pk_add_f32 v[20:21], v[20:21], 1.0 op_sel_hi:[1,0]
	v_pk_add_f32 v[24:25], v[24:25], 1.0 op_sel_hi:[1,0]
	v_pk_add_f32 v[22:23], v[22:23], 1.0 op_sel_hi:[1,0]
	v_pk_add_f32 v[26:27], v[26:27], 1.0 op_sel_hi:[1,0]
	v_rcp_f32_e32 v20, v20
	v_rcp_f32_e32 v24, v24
	v_rcp_f32_e32 v21, v21
	v_rcp_f32_e32 v25, v25
	v_rcp_f32_e32 v22, v22
	v_rcp_f32_e32 v26, v26
	v_rcp_f32_e32 v23, v23
	v_rcp_f32_e32 v27, v27
	v_pk_mul_f32 v[20:21], v[20:21], s[62:63] op_sel_hi:[1,0]
	v_pk_mul_f32 v[24:25], v[24:25], s[62:63] op_sel_hi:[1,0]
	v_pk_mul_f32 v[22:23], v[22:23], s[62:63] op_sel_hi:[1,0]
	v_pk_mul_f32 v[26:27], v[26:27], s[62:63] op_sel_hi:[1,0]
	v_cvt_pk_u8_f32 v30, v20, 0, 0
	v_cvt_pk_u8_f32 v31, v24, 0, 0
	v_cvt_pk_u8_f32 v30, v21, 1, v30
	v_cvt_pk_u8_f32 v31, v25, 1, v31
	v_cvt_pk_u8_f32 v30, v22, 2, v30
	v_cvt_pk_u8_f32 v31, v26, 2, v31
	v_cvt_pk_u8_f32 v30, v23, 3, v30
	v_cvt_pk_u8_f32 v31, v27, 3, v31
	global_store_dwordx2 v[170:171], v[30:31], off offset:2048
	v_pk_fma_f32 v[20:21], v[46:47], s[98:99], v[4:5] op_sel_hi:[1,0,1]
	v_pk_fma_f32 v[24:25], v[42:43], s[98:99], v[0:1] op_sel_hi:[1,0,1]
	v_pk_fma_f32 v[22:23], v[48:49], s[98:99], v[6:7] op_sel_hi:[1,0,1]
	v_pk_fma_f32 v[26:27], v[44:45], s[98:99], v[2:3] op_sel_hi:[1,0,1]
	v_exp_f32_e32 v20, v20
	v_exp_f32_e32 v24, v24
	v_exp_f32_e32 v21, v21
	v_exp_f32_e32 v25, v25
	v_exp_f32_e32 v22, v22
	v_exp_f32_e32 v26, v26
	v_exp_f32_e32 v23, v23
	v_exp_f32_e32 v27, v27
	v_pk_add_f32 v[20:21], v[20:21], 1.0 op_sel_hi:[1,0]
	v_pk_add_f32 v[24:25], v[24:25], 1.0 op_sel_hi:[1,0]
	v_pk_add_f32 v[22:23], v[22:23], 1.0 op_sel_hi:[1,0]
; #define LAS __attribute__((address_space(3)))
; __device__ __forceinline__ u32x4 pk8(const f32x4 v0, const f32x4 v1) { u32x4 w; w.x = pk_f16(v0[0], v0[1]); w.y = pk_f16(v0[2], v0[3]); w.z = pk_f16(v1[0], v1[1]); w.w = pk_f16(v1[2], v1[3]); return w; }
; __device__ __forceinline__ float sigmoidf_(float x) { return __builtin_amdgcn_rcpf(1.0f + __expf(-x)); }
; __device__ __forceinline__ f32x4 sig4(const f32x4 v) { return (f32x4){sigmoidf_(v[0]), sigmoidf_(v[1]), sigmoidf_(v[2]), sigmoidf_(v[3])}; }
;     __device__ __forceinline__ void operator()(const f32x4 (&acc)[2][2][4][2], const GUnit& u, int wr, int wc, int fr, int fq, LAS unsigned char*) const {
;         const int grow0 = u.pm * 256 + wr * 64 + fr, gcol0 = u.pn * 256 + wc * 32 + 8 * fq;
;         unsigned char* base = ws + B_SG; const float* bias = b_in + gcol0;
;         f32x4 bv[2][2];
;         const bool qk = u.kind != K_SG;
; #pragma unroll
;         for (int bj = 0; bj < 2; ++bj)
; #pragma unroll
;             for (int n = 0; n < 2; ++n) bv[bj][n] = *(const f32x4*)(bias + bj * 128 + 4 * n);
; #pragma unroll
;         for (int ai = 0; ai < 2; ++ai)
; #pragma unroll
;             for (int m = 0; m < 4; ++m) { unsigned char* rowp = base + (size_t)(grow0 + ai * 128 + m * 16) * 2048 + (gcol0 - 2048);
;                 if (qk) { f16* qp = (f16*)(ws + (u.kind == K_Q ? B_Q : B_K)) + (size_t)(grow0 + ai * 128 + m * 16) * 512 + (gcol0 & 511);
; #pragma unroll
;                     for (int bj = 0; bj < 2; ++bj) *(u32x4*)(qp + bj * 128) = pk8(acc[ai][bj][m][0] + bv[bj][0], acc[ai][bj][m][1] + bv[bj][1]);
;                     continue; }
; #pragma unroll
;                 for (int bj = 0; bj < 2; ++bj) { f32x4 v0 = sig4(acc[ai][bj][m][0] + bv[bj][0]) * 255.0f, v1 = sig4(acc[ai][bj][m][1] + bv[bj][1]) * 255.0f; u32x2 o = {0u, 0u};
;                     o.x = __builtin_amdgcn_cvt_pk_u8_f32(v0[0], 0, o.x); o.x = __builtin_amdgcn_cvt_pk_u8_f32(v0[1], 1, o.x); o.x = __builtin_amdgcn_cvt_pk_u8_f32(v0[2], 2, o.x); o.x = __builtin_amdgcn_cvt_pk_u8_f32(v0[3], 3, o.x);
;                     o.y = __builtin_amdgcn_cvt_pk_u8_f32(v1[0], 0, o.y); o.y = __builtin_amdgcn_cvt_pk_u8_f32(v1[1], 1, o.y); o.y = __builtin_amdgcn_cvt_pk_u8_f32(v1[2], 2, o.y); o.y = __builtin_amdgcn_cvt_pk_u8_f32(v1[3], 3, o.y);
;                     *(u32x2*)(rowp + bj * 128) = o; } }
;     }
	v_pk_add_f32 v[26:27], v[26:27], 1.0 op_sel_hi:[1,0]
	v_rcp_f32_e32 v20, v20
	v_rcp_f32_e32 v24, v24
	v_rcp_f32_e32 v21, v21
	v_rcp_f32_e32 v25, v25
	v_rcp_f32_e32 v22, v22
	v_rcp_f32_e32 v26, v26
	v_rcp_f32_e32 v23, v23
	v_rcp_f32_e32 v27, v27
	v_pk_mul_f32 v[20:21], v[20:21], s[62:63] op_sel_hi:[1,0]
	v_pk_mul_f32 v[24:25], v[24:25], s[62:63] op_sel_hi:[1,0]
	v_pk_mul_f32 v[22:23], v[22:23], s[62:63] op_sel_hi:[1,0]
	v_pk_mul_f32 v[26:27], v[26:27], s[62:63] op_sel_hi:[1,0]
	v_cvt_pk_u8_f32 v28, v20, 0, 0
	v_cvt_pk_u8_f32 v29, v24, 0, 0
	v_cvt_pk_u8_f32 v28, v21, 1, v28
	v_cvt_pk_u8_f32 v29, v25, 1, v29
	v_cvt_pk_u8_f32 v28, v22, 2, v28
	v_cvt_pk_u8_f32 v29, v26, 2, v29
	v_cvt_pk_u8_f32 v28, v23, 3, v28
	v_cvt_pk_u8_f32 v29, v27, 3, v29
	global_store_dwordx2 v[170:171], v[28:29], off offset:2176
	v_add_co_u32_e32 v170, vcc, 0x58000, v168
	v_addc_co_u32_e32 v171, vcc, 0, v169, vcc
	v_pk_fma_f32 v[20:21], v[70:71], s[98:99], v[12:13] op_sel_hi:[1,0,1]
	v_pk_fma_f32 v[24:25], v[66:67], s[98:99], v[8:9] op_sel_hi:[1,0,1]
	v_pk_fma_f32 v[22:23], v[72:73], s[98:99], v[14:15] op_sel_hi:[1,0,1]
	v_pk_fma_f32 v[26:27], v[68:69], s[98:99], v[10:11] op_sel_hi:[1,0,1]
	v_exp_f32_e32 v20, v20
	v_exp_f32_e32 v24, v24
	v_exp_f32_e32 v21, v21
	v_exp_f32_e32 v25, v25
	v_exp_f32_e32 v22, v22
	v_exp_f32_e32 v26, v26
	v_exp_f32_e32 v23, v23
	v_exp_f32_e32 v27, v27
	v_pk_add_f32 v[20:21], v[20:21], 1.0 op_sel_hi:[1,0]
	v_pk_add_f32 v[24:25], v[24:25], 1.0 op_sel_hi:[1,0]
	v_pk_add_f32 v[22:23], v[22:23], 1.0 op_sel_hi:[1,0]
	v_pk_add_f32 v[26:27], v[26:27], 1.0 op_sel_hi:[1,0]
	v_rcp_f32_e32 v20, v20
	v_rcp_f32_e32 v24, v24
	v_rcp_f32_e32 v21, v21
	v_rcp_f32_e32 v25, v25
	v_rcp_f32_e32 v22, v22
	v_rcp_f32_e32 v26, v26
	v_rcp_f32_e32 v23, v23
	v_rcp_f32_e32 v27, v27
	v_pk_mul_f32 v[20:21], v[20:21], s[62:63] op_sel_hi:[1,0]
	v_pk_mul_f32 v[24:25], v[24:25], s[62:63] op_sel_hi:[1,0]
	v_pk_mul_f32 v[22:23], v[22:23], s[62:63] op_sel_hi:[1,0]
	v_pk_mul_f32 v[26:27], v[26:27], s[62:63] op_sel_hi:[1,0]
	v_cvt_pk_u8_f32 v30, v20, 0, 0
	v_cvt_pk_u8_f32 v31, v24, 0, 0
	v_cvt_pk_u8_f32 v30, v21, 1, v30
	v_cvt_pk_u8_f32 v31, v25, 1, v31
	v_cvt_pk_u8_f32 v30, v22, 2, v30
	v_cvt_pk_u8_f32 v31, v26, 2, v31
	v_cvt_pk_u8_f32 v30, v23, 3, v30
	v_cvt_pk_u8_f32 v31, v27, 3, v31
	global_store_dwordx2 v[170:171], v[30:31], off offset:2048
	v_pk_fma_f32 v[20:21], v[38:39], s[98:99], v[4:5] op_sel_hi:[1,0,1]
	v_pk_fma_f32 v[24:25], v[34:35], s[98:99], v[0:1] op_sel_hi:[1,0,1]
	v_pk_fma_f32 v[22:23], v[40:41], s[98:99], v[6:7] op_sel_hi:[1,0,1]
	v_pk_fma_f32 v[26:27], v[36:37], s[98:99], v[2:3] op_sel_hi:[1,0,1]
	v_exp_f32_e32 v20, v20
	v_exp_f32_e32 v24, v24
	v_exp_f32_e32 v21, v21
	v_exp_f32_e32 v25, v25
	v_exp_f32_e32 v22, v22
	v_exp_f32_e32 v26, v26
	v_exp_f32_e32 v23, v23
	v_exp_f32_e32 v27, v27
	v_pk_add_f32 v[20:21], v[20:21], 1.0 op_sel_hi:[1,0]
	v_pk_add_f32 v[24:25], v[24:25], 1.0 op_sel_hi:[1,0]
	v_pk_add_f32 v[22:23], v[22:23], 1.0 op_sel_hi:[1,0]
	v_pk_add_f32 v[26:27], v[26:27], 1.0 op_sel_hi:[1,0]
	v_rcp_f32_e32 v20, v20
	v_rcp_f32_e32 v24, v24
	v_rcp_f32_e32 v21, v21
	v_rcp_f32_e32 v25, v25
	v_rcp_f32_e32 v22, v22
	v_rcp_f32_e32 v26, v26
	v_rcp_f32_e32 v23, v23
	v_rcp_f32_e32 v27, v27
	v_pk_mul_f32 v[20:21], v[20:21], s[62:63] op_sel_hi:[1,0]
	v_pk_mul_f32 v[24:25], v[24:25], s[62:63] op_sel_hi:[1,0]
	v_pk_mul_f32 v[22:23], v[22:23], s[62:63] op_sel_hi:[1,0]
	v_pk_mul_f32 v[26:27], v[26:27], s[62:63] op_sel_hi:[1,0]
	v_cvt_pk_u8_f32 v28, v20, 0, 0
	v_cvt_pk_u8_f32 v29, v24, 0, 0
	v_cvt_pk_u8_f32 v28, v21, 1, v28
	v_cvt_pk_u8_f32 v29, v25, 1, v29
	v_cvt_pk_u8_f32 v28, v22, 2, v28
	v_cvt_pk_u8_f32 v29, v26, 2, v29
	v_cvt_pk_u8_f32 v28, v23, 3, v28
	v_cvt_pk_u8_f32 v29, v27, 3, v29
	global_store_dwordx2 v[170:171], v[28:29], off offset:2176
	s_branch .LBB0_106
